# pass C gain-load hoist + 20-byte pad so the W_out/W_up/W_down K-loop heads keep the byte phase (mod 64) of the previous best
# speedup vs baseline: 1.0006x; 1.0006x over previous
; __device__ __forceinline__ void xcd_barrier(const XcdBarrier& b) {
;     asm volatile("s_waitcnt vmcnt(0)" ::: "memory");
;     __syncthreads();
;     if (threadIdx.x == 0) {
;         unsigned* bar = b.bar;
;         __builtin_amdgcn_s_waitcnt(0);
;         unsigned nloc = b.st[0], nx = b.st[1];
;         if (nloc == 0u) { xcd_barrier_complete(bar, b.x, nloc, nx); b.st[0] = nloc; b.st[1] = nx; }
.LBB0_488:
	s_nop 0
	s_nop 0
	s_nop 0
	s_nop 0
	s_nop 0
	s_waitcnt vmcnt(0)
	s_barrier
	s_mov_b64 s[2:3], exec
	v_readlane_b32 s4, v246, 2
	v_readlane_b32 s5, v246, 3
	s_and_b64 s[4:5], s[2:3], s[4:5]
	s_mov_b64 exec, s[4:5]
	s_cbranch_execz .LBB0_540
	v_readlane_b32 s4, v245, 56
	s_waitcnt vmcnt(0) expcnt(0) lgkmcnt(0)
	s_nop 0
	v_mov_b32_e32 v0, s4
	ds_read_b32 v2, v0
	v_readlane_b32 s4, v245, 57
	s_waitcnt lgkmcnt(0)
	v_cmp_ne_u32_e32 vcc, 0, v2
	v_mov_b32_e32 v0, s4
	ds_read_b32 v0, v0
	s_cbranch_vccnz .LBB0_504
	s_mov_b32 s10, 1
	s_branch .LBB0_492
